# stack12: stack11 + flag barrier after phase 0 without the release write-back (phase-0 stores are write-through)
# speedup vs baseline: 1.0508x; 1.0058x over previous
; template <bool COOP>
; __global__ void __launch_bounds__(512) mk_kernel(Params p, int ph_lo, int ph_hi) {
;     ...
;         if (COOP && ph + 1 < ph_hi) {
;             if (ph == 0) cg::this_grid().sync();
;             else grid_barrier(p.bar, (unsigned)ph);
.LBB0_433:
	s_and_b64 vcc, exec, s[4:5]
	s_cbranch_vccz .LBB0_4
	s_waitcnt vmcnt(0) lgkmcnt(0)
	s_barrier
	v_readfirstlane_b32 s6, v252
	s_nop 3
	s_cmp_lt_u32 s6, 64
	s_cbranch_scc0 .Lfb_others
	s_nop 0
	s_waitcnt vmcnt(0)
	v_readlane_b32 s7, v253, 0
	s_nop 3
	s_lshl_b32 s7, s7, 2
	v_mov_b32_e32 v0, s7
	v_mov_b32_e32 v1, 0x600df1a6
	s_mov_b64 s[8:9], exec
	s_mov_b64 exec, 1
	global_store_dword v0, v1, s[80:81] offset:3072 sc0 sc1
	s_mov_b64 exec, s[8:9]
	s_waitcnt vmcnt(0)
	v_and_b32_e32 v2, 63, v252
	v_lshlrev_b32_e32 v2, 2, v2
	s_mov_b32 s7, 0x100000
